# candE + stream near-rows loop: next iteration's 8 cache rows prefetched into spare VGPRs, single counted wait at loop top
# speedup vs baseline: 1.0040x; 1.0040x over previous
; __device__ __forceinline__ float bf_lo(unsigned w) { return __uint_as_float(w << 16); }
; __device__ __forceinline__ float bf_hi(unsigned w) { return __uint_as_float(w & 0xffff0000u); }
; __device__ __forceinline__ float row_sum_f(float v) { v += dpp_f<0x128>(v); v += dpp_f<0x124>(v); v += dpp_f<0x122>(v); v += dpp_f<0x121>(v); return v; }
; __device__ __forceinline__ void stream_task(const Args& a, const int task, const int wave, const float kbA, LAS unsigned* rb, unsigned& ep) {
;     ...
;             f32x4 q[8], O[8]; float M[8], l[8];
; #pragma unroll
;             for (int i = 0; i < 8; ++i) {
;                 const u32x2 qr = *(const u32x2*)(QA + (size_t)(NTP + b * DS + i) * 512 + hd * 64 + dl);
;                 q[i] = (f32x4){bf_lo(qr.x), bf_hi(qr.x), bf_lo(qr.y), bf_hi(qr.y)};
;                 M[i] = sqrtf(row_sum_f(q[i][0] * q[i][0] + q[i][1] * q[i][1] + q[i][2] * q[i][2] + q[i][3] * q[i][3])) * kbA;
;                 O[i] = (f32x4){0.f, 0.f, 0.f, 0.f}; l[i] = 0.f;
;             }
;     ...
; #pragma unroll 1
;             for (int n0 = 480; n0 < 512; n0 += 4) {
;                 f32x4 k4[4], v4[4];
; #pragma unroll
;                 for (int u = 0; u < 4; ++u) { const size_t ro = (size_t)(wave + 4 * (n0 + u)) * 512; k4[u] = __builtin_nontemporal_load((const f32x4*)(kc + ro)); v4[u] = __builtin_nontemporal_load((const f32x4*)(vc + ro)); }
.LBB0_1163:
	s_lshl_b32 s0, s35, 6
	s_and_b32 s0, s0, 0x100
	v_or_b32_e32 v66, s0, v179
	v_lshl_add_u64 v[2:3], v[92:93], 0, s[16:17]
	v_lshl_add_u64 v[2:3], v[2:3], 0, v[66:67]
	v_lshlrev_b64 v[152:153], 2, v[2:3]
	v_mov_b32_e32 v2, 0
	s_movk_i32 s2, 0x1dc
	s_mov_b64 s[16:17], s[70:71]
	s_mov_b64 s[18:19], s[68:69]
	v_readlane_b32 s20, v240, 26
	v_readlane_b32 s55, v240, 23
	s_mov_b64 s[88:89], s[66:67]
	v_mov_b32_e32 v3, v2
	v_mov_b32_e32 v4, v2
	v_mov_b32_e32 v5, v2
	s_waitcnt vmcnt(8)
	v_mov_b32_e32 v6, v2
	v_mov_b32_e32 v7, v2
	v_mov_b32_e32 v8, v2
	v_mov_b32_e32 v9, v2
	v_mov_b32_e32 v10, v2
	v_mov_b32_e32 v11, v2
	v_mov_b32_e32 v12, v2
	v_mov_b32_e32 v13, v2
	v_mov_b32_e32 v14, v2
	v_mov_b32_e32 v15, v2
	v_mov_b32_e32 v16, v2
	v_mov_b32_e32 v17, v2
	v_mov_b32_e32 v18, v2
	v_mov_b32_e32 v19, v2
	v_mov_b32_e32 v20, v2
	v_mov_b32_e32 v21, v2
	v_mov_b32_e32 v22, v2
	v_mov_b32_e32 v23, v2
	v_mov_b32_e32 v24, v2
	v_mov_b32_e32 v25, v2
	v_mov_b32_e32 v26, v2
	v_mov_b32_e32 v27, v2
	v_mov_b32_e32 v28, v2
	v_mov_b32_e32 v29, v2
	s_waitcnt vmcnt(7)
	v_mov_b32_e32 v30, v2
	v_mov_b32_e32 v31, v2
	v_mov_b32_e32 v32, v2
	v_mov_b32_e32 v33, v2
	v_mov_b32_e32 v86, v2
	v_mov_b32_e32 v87, v2
	v_mov_b32_e32 v148, v2
	v_mov_b32_e32 v149, v2
	v_mov_b32_e32 v150, v2
	v_mov_b32_e32 v151, v2
	v_mov_b32_e32 v84, v2
	v_mov_b32_e32 v85, v2
	v_lshl_add_u64 v[232:233], s[18:19], 0, v[152:153]
	v_lshl_add_u64 v[234:235], s[16:17], 0, v[152:153]
	v_add_co_u32_e32 v236, vcc, s22, v232
	s_nop 1
	v_addc_co_u32_e32 v237, vcc, 0, v233, vcc
	global_load_dwordx4 v[200:203], v[236:237], off nt
	v_add_co_u32_e32 v236, vcc, s22, v234
	s_nop 1
	v_addc_co_u32_e32 v237, vcc, 0, v235, vcc
	global_load_dwordx4 v[204:207], v[236:237], off nt
	v_add_co_u32_e32 v236, vcc, s23, v232
	s_nop 1
	v_addc_co_u32_e32 v237, vcc, 0, v233, vcc
	global_load_dwordx4 v[208:211], v[236:237], off nt
	v_add_co_u32_e32 v236, vcc, s23, v234
	s_nop 1
	v_addc_co_u32_e32 v237, vcc, 0, v235, vcc
	global_load_dwordx4 v[212:215], v[236:237], off nt
	v_add_co_u32_e32 v236, vcc, s10, v232
	s_nop 1
	v_addc_co_u32_e32 v237, vcc, 0, v233, vcc
	global_load_dwordx4 v[216:219], v[236:237], off nt
	v_add_co_u32_e32 v236, vcc, s10, v234
	s_nop 1
	v_addc_co_u32_e32 v237, vcc, 0, v235, vcc
	global_load_dwordx4 v[220:223], v[236:237], off nt
	v_add_co_u32_e32 v236, vcc, s31, v232
	s_nop 1
	v_addc_co_u32_e32 v237, vcc, 0, v233, vcc
	global_load_dwordx4 v[224:227], v[236:237], off nt
	v_add_co_u32_e32 v236, vcc, s31, v234
	s_nop 1
	v_addc_co_u32_e32 v237, vcc, 0, v235, vcc
	global_load_dwordx4 v[228:231], v[236:237], off nt
	s_waitcnt vmcnt(0)
	s_branch .Lnear_copy
.LBB0_1164:
	s_waitcnt vmcnt(8)
; __device__ __forceinline__ float row_sum_f(float v) { v += dpp_f<0x128>(v); v += dpp_f<0x124>(v); v += dpp_f<0x122>(v); v += dpp_f<0x121>(v); return v; }
; __device__ __forceinline__ void stream_task(const Args& a, const int task, const int wave, const float kbA, LAS unsigned* rb, unsigned& ep) {
;     ...
;             for (int n0 = 480; n0 < 512; n0 += 4) {
;                 f32x4 k4[4], v4[4];
; #pragma unroll
;                 for (int u = 0; u < 4; ++u) { const size_t ro = (size_t)(wave + 4 * (n0 + u)) * 512; k4[u] = __builtin_nontemporal_load((const f32x4*)(kc + ro)); v4[u] = __builtin_nontemporal_load((const f32x4*)(vc + ro)); }
; #pragma unroll
;                 for (int u = 0; u < 4; ++u) {
;                     const int r = wave + 4 * (n0 + u);
;                     { const size_t wo = (size_t)(r - DS) * 512; __builtin_nontemporal_store(k4[u], (f32x4*)(ko + wo)); __builtin_nontemporal_store(v4[u], (f32x4*)(vo + wo)); }
; #pragma unroll
;                     for (int i = 0; i < 8; ++i) {
;                         const int dist = LA + i - r;
;                         const int mult = (dist <= 128 ? 1 : 0) + ((dist & 3) == 0 ? 1 : 0) + ((dist & 15) == 0 ? 1 : 0);
;                         if (mult) {
;                             const float dot = row_sum_f(q[i][0] * k4[u][0] + q[i][1] * k4[u][1] + q[i][2] * k4[u][2] + q[i][3] * k4[u][3]);
;                             const float pp = __builtin_amdgcn_exp2f(dot - slope2 * (float)dist - M[i]) * (float)mult;
;                             l[i] += pp; O[i] = O[i] + v4[u] * pp;
;                         }
.Lnear_copy:
	v_mov_b64_e32 v[80:81], v[200:201]
	v_mov_b64_e32 v[82:83], v[202:203]
	v_mov_b64_e32 v[76:77], v[204:205]
	v_mov_b64_e32 v[78:79], v[206:207]
	v_mov_b64_e32 v[62:63], v[208:209]
	v_mov_b64_e32 v[64:65], v[210:211]
	v_mov_b64_e32 v[58:59], v[212:213]
	v_mov_b64_e32 v[60:61], v[214:215]
	v_mov_b64_e32 v[54:55], v[216:217]
	v_mov_b64_e32 v[56:57], v[218:219]
	v_mov_b64_e32 v[46:47], v[220:221]
	v_mov_b64_e32 v[48:49], v[222:223]
	v_mov_b64_e32 v[50:51], v[224:225]
	v_mov_b64_e32 v[52:53], v[226:227]
	v_mov_b64_e32 v[42:43], v[228:229]
	v_mov_b64_e32 v[44:45], v[230:231]
	v_lshl_add_u64 v[154:155], s[88:89], 0, v[152:153]
	s_add_i32 s47, s55, -7
	v_pk_mul_f32 v[194:195], v[82:83], v[40:41]
	s_cmpk_lt_u32 s2, 0x1f8
	s_cbranch_scc0 .Lnear_nopf
	s_add_u32 s0, s18, 0x8000
	s_addc_u32 s1, s19, 0
	v_lshl_add_u64 v[232:233], s[0:1], 0, v[152:153]
	s_add_u32 s0, s16, 0x8000
	s_addc_u32 s1, s17, 0
	v_lshl_add_u64 v[234:235], s[0:1], 0, v[152:153]
	v_add_co_u32_e32 v236, vcc, s22, v232
	s_nop 1
	v_addc_co_u32_e32 v237, vcc, 0, v233, vcc
	global_load_dwordx4 v[200:203], v[236:237], off nt
	v_add_co_u32_e32 v236, vcc, s22, v234
	s_nop 1
	v_addc_co_u32_e32 v237, vcc, 0, v235, vcc
	global_load_dwordx4 v[204:207], v[236:237], off nt
	v_add_co_u32_e32 v236, vcc, s23, v232
	s_nop 1
	v_addc_co_u32_e32 v237, vcc, 0, v233, vcc
	global_load_dwordx4 v[208:211], v[236:237], off nt
	v_add_co_u32_e32 v236, vcc, s23, v234
	s_nop 1
	v_addc_co_u32_e32 v237, vcc, 0, v235, vcc
	global_load_dwordx4 v[212:215], v[236:237], off nt
	v_add_co_u32_e32 v236, vcc, s10, v232
	s_nop 1
	v_addc_co_u32_e32 v237, vcc, 0, v233, vcc
	global_load_dwordx4 v[216:219], v[236:237], off nt
	v_add_co_u32_e32 v236, vcc, s10, v234
	s_nop 1
	v_addc_co_u32_e32 v237, vcc, 0, v235, vcc
	global_load_dwordx4 v[220:223], v[236:237], off nt
	v_add_co_u32_e32 v236, vcc, s31, v232
	s_nop 1
	v_addc_co_u32_e32 v237, vcc, 0, v233, vcc
	global_load_dwordx4 v[224:227], v[236:237], off nt
	v_add_co_u32_e32 v236, vcc, s31, v234
	s_nop 1
	v_addc_co_u32_e32 v237, vcc, 0, v235, vcc
	global_load_dwordx4 v[228:231], v[236:237], off nt
.Lnear_nopf:
	s_mov_b32 s0, 0x683c000
	v_add_co_u32_e32 v192, vcc, s0, v154
	s_mov_b32 s0, 0x2683c000
	s_nop 0
	v_addc_co_u32_e32 v193, vcc, 0, v155, vcc
	global_store_dwordx4 v[192:193], v[80:83], off nt
	v_add_co_u32_e32 v192, vcc, s0, v154
	s_and_b32 s0, s47, 3
	s_nop 0
	v_addc_co_u32_e32 v193, vcc, 0, v155, vcc
	global_store_dwordx4 v[192:193], v[76:79], off nt
	v_pk_mul_f32 v[192:193], v[80:81], v[38:39]
	s_cmp_eq_u32 s0, 0
	v_add_f32_e32 v66, v192, v193
	v_add_f32_e32 v66, v194, v66
	v_add_f32_e32 v66, v195, v66
	v_cvt_f32_i32_e32 v193, s47
	s_cselect_b32 s61, 2, 1
	v_add_f32_dpp v66, v66, v66 row_ror:8 row_mask:0xf bank_mask:0xf bound_ctrl:1
	s_and_b32 s0, s47, 15
	s_cmp_eq_u32 s0, 0
	v_add_f32_dpp v66, v66, v66 row_ror:4 row_mask:0xf bank_mask:0xf bound_ctrl:1
	s_cselect_b64 s[0:1], -1, 0
	s_cmp_lg_u64 s[0:1], 0
	v_add_f32_dpp v66, v66, v66 row_ror:2 row_mask:0xf bank_mask:0xf bound_ctrl:1
	s_addc_u32 s0, s61, 0
	s_add_i32 s47, s55, -6
	v_add_f32_dpp v66, v66, v66 row_ror:1 row_mask:0xf bank_mask:0xf bound_ctrl:1
	v_fma_f32 v66, -v184, v193, v66
	v_sub_f32_e32 v66, v66, v191
	v_exp_f32_e32 v66, v66
	s_cmpk_gt_u32 s20, 0x780
	v_cvt_f32_ubyte0_e32 v114, s0
	s_cselect_b64 s[0:1], -1, 0
	v_mul_f32_e32 v66, v66, v114
	v_cndmask_b32_e64 v114, 0, 1, s[0:1]
	s_and_b32 s0, s47, 3
	s_cmp_eq_u32 s0, 0
	s_cselect_b64 s[0:1], -1, 0
	v_cndmask_b32_e64 v192, 0, 1, s[0:1]
	s_and_b32 s0, s47, 15
	s_cmp_eq_u32 s0, 0
	s_cselect_b64 vcc, -1, 0
	v_addc_co_u32_e32 v192, vcc, v192, v114, vcc
	v_cvt_f32_i32_e32 v114, s47
	v_cmp_ne_u32_e32 vcc, 0, v192
	v_pk_fma_f32 v[4:5], v[78:79], v[66:67], v[4:5] op_sel_hi:[1,0,1]
	v_pk_fma_f32 v[2:3], v[76:77], v[66:67], v[2:3] op_sel_hi:[1,0,1]
	s_cbranch_vccz .LBB0_1166
	v_pk_mul_f32 v[194:195], v[80:81], v[34:35]
	v_pk_mul_f32 v[196:197], v[82:83], v[36:37]
	v_add_f32_e32 v194, v194, v195
	v_add_f32_e32 v194, v196, v194
	v_add_f32_e32 v194, v197, v194
	v_cvt_f32_ubyte0_e32 v195, v192
	s_nop 0
	v_add_f32_dpp v194, v194, v194 row_ror:8 row_mask:0xf bank_mask:0xf bound_ctrl:1
	s_nop 1
	v_add_f32_dpp v194, v194, v194 row_ror:4 row_mask:0xf bank_mask:0xf bound_ctrl:1
	s_nop 1
	v_add_f32_dpp v194, v194, v194 row_ror:2 row_mask:0xf bank_mask:0xf bound_ctrl:1
	s_nop 1
	v_add_f32_dpp v194, v194, v194 row_ror:1 row_mask:0xf bank_mask:0xf bound_ctrl:1
	v_fma_f32 v194, -v184, v114, v194
	v_sub_f32_e32 v194, v194, v190
	v_exp_f32_e32 v194, v194
	s_nop 0
	v_mul_f32_e32 v192, v194, v195
	v_fmac_f32_e32 v87, v194, v195
	v_pk_fma_f32 v[8:9], v[78:79], v[192:193], v[8:9] op_sel_hi:[1,0,1]
	v_pk_fma_f32 v[6:7], v[76:77], v[192:193], v[6:7] op_sel_hi:[1,0,1]

; __device__ __forceinline__ float row_sum_f(float v) { v += dpp_f<0x128>(v); v += dpp_f<0x124>(v); v += dpp_f<0x122>(v); v += dpp_f<0x121>(v); return v; }
; __device__ __forceinline__ void stream_task(const Args& a, const int task, const int wave, const float kbA, LAS unsigned* rb, unsigned& ep) {
;     ...
; #pragma unroll
;                 for (int u = 0; u < 4; ++u) {
;                     const int r = wave + 4 * (n0 + u);
;                     { const size_t wo = (size_t)(r - DS) * 512; __builtin_nontemporal_store(k4[u], (f32x4*)(ko + wo)); __builtin_nontemporal_store(v4[u], (f32x4*)(vo + wo)); }
; #pragma unroll
;                     for (int i = 0; i < 8; ++i) {
;                         const int dist = LA + i - r;
;                         const int mult = (dist <= 128 ? 1 : 0) + ((dist & 3) == 0 ? 1 : 0) + ((dist & 15) == 0 ? 1 : 0);
;                         if (mult) {
;                             const float dot = row_sum_f(q[i][0] * k4[u][0] + q[i][1] * k4[u][1] + q[i][2] * k4[u][2] + q[i][3] * k4[u][3]);
;                             const float pp = __builtin_amdgcn_exp2f(dot - slope2 * (float)dist - M[i]) * (float)mult;
;                             l[i] += pp; O[i] = O[i] + v4[u] * pp;
;                         }
.LBB0_1178:
	v_add_co_u32_e32 v76, vcc, 0x683e000, v154
	v_pk_mul_f32 v[78:79], v[64:65], v[40:41]
	v_addc_co_u32_e32 v77, vcc, 0, v155, vcc
	global_store_dwordx4 v[76:77], v[62:65], off nt
	v_add_co_u32_e32 v76, vcc, 0x2683e000, v154
	s_sub_i32 s90, 0x7fc, s20
	s_nop 0
	v_addc_co_u32_e32 v77, vcc, 0, v155, vcc
	global_store_dwordx4 v[76:77], v[58:61], off nt
	v_pk_mul_f32 v[76:77], v[62:63], v[38:39]
	v_pk_mul_f32 v[80:81], v[64:65], v[36:37]
	v_add_f32_e32 v76, v76, v77
	v_add_f32_e32 v76, v78, v76
	v_add_f32_e32 v76, v79, v76
	v_cvt_f32_i32_e32 v77, s90
	v_pk_mul_f32 v[78:79], v[62:63], v[34:35]
	v_add_f32_dpp v76, v76, v76 row_ror:8 row_mask:0xf bank_mask:0xf bound_ctrl:1
	s_sub_i32 s91, 0x7fd, s20
	s_mov_b32 s61, s60
	v_add_f32_dpp v76, v76, v76 row_ror:4 row_mask:0xf bank_mask:0xf bound_ctrl:1
	s_add_i32 s0, s20, 4
	v_pk_mul_f32 v[82:83], v[62:63], v[136:137]
	v_add_f32_dpp v76, v76, v76 row_ror:2 row_mask:0xf bank_mask:0xf bound_ctrl:1
	v_pk_mul_f32 v[196:197], v[64:65], v[138:139]
	v_pk_mul_f32 v[198:199], v[64:65], v[130:131]
	v_add_f32_dpp v76, v76, v76 row_ror:1 row_mask:0xf bank_mask:0xf bound_ctrl:1
	v_fma_f32 v76, -v184, v77, v76
	v_add_f32_e32 v77, v78, v79
	v_add_f32_e32 v77, v80, v77
	v_add_f32_e32 v77, v81, v77
	v_cvt_f32_i32_e32 v78, s91
	s_and_b64 s[90:91], s[90:91], s[60:61]
	v_add_f32_dpp v77, v77, v77 row_ror:8 row_mask:0xf bank_mask:0xf bound_ctrl:1
	s_cmp_eq_u32 s91, 0
	s_cselect_b64 vcc, -1, 0
	v_add_f32_dpp v77, v77, v77 row_ror:4 row_mask:0xf bank_mask:0xf bound_ctrl:1
	s_cmp_eq_u32 s90, 0
	s_cselect_b64 s[90:91], -1, 0
	v_add_f32_dpp v77, v77, v77 row_ror:2 row_mask:0xf bank_mask:0xf bound_ctrl:1
	v_sub_f32_e32 v76, v76, v191
	s_cmp_lg_u64 s[90:91], 0
	v_add_f32_dpp v77, v77, v77 row_ror:1 row_mask:0xf bank_mask:0xf bound_ctrl:1
	v_fma_f32 v77, -v184, v78, v77
	v_sub_f32_e32 v77, v77, v190
	v_exp_f32_e32 v76, v76
	v_exp_f32_e32 v77, v77
	s_addc_u32 s1, s97, 0
	s_cmp_lg_u64 vcc, 0
	s_addc_u32 s47, s96, 0
	v_cvt_f32_ubyte0_e32 v78, s1
	s_add_i32 s1, s55, -9
	v_cvt_f32_ubyte0_e32 v79, s47
	s_and_b32 s47, s1, 15
	v_pk_mul_f32 v[76:77], v[76:77], v[78:79]
	s_cmp_eq_u32 s47, 0
	v_pk_mul_f32 v[78:79], v[62:63], v[142:143]
	s_cselect_b64 s[90:91], -1, 0
	v_pk_mul_f32 v[80:81], v[64:65], v[140:141]
	v_add_f32_e32 v78, v78, v79
	v_add_f32_e32 v79, v82, v83
	s_cmp_lg_u64 s[90:91], 0
	v_add_f32_e32 v78, v80, v78
	v_add_f32_e32 v79, v196, v79
	s_addc_u32 s47, s29, 0
	v_add_f32_e32 v78, v81, v78
	v_cvt_f32_i32_e32 v81, s1
	s_add_i32 s1, s55, -8
	v_add_f32_e32 v79, v197, v79
	v_add_f32_dpp v78, v78, v78 row_ror:8 row_mask:0xf bank_mask:0xf bound_ctrl:1
	v_cvt_f32_i32_e32 v82, s1
	v_add_f32_dpp v79, v79, v79 row_ror:8 row_mask:0xf bank_mask:0xf bound_ctrl:1
	v_add_f32_dpp v78, v78, v78 row_ror:4 row_mask:0xf bank_mask:0xf bound_ctrl:1
	s_and_b32 s61, s1, 3
	v_add_f32_dpp v79, v79, v79 row_ror:4 row_mask:0xf bank_mask:0xf bound_ctrl:1
	v_add_f32_dpp v78, v78, v78 row_ror:2 row_mask:0xf bank_mask:0xf bound_ctrl:1
	s_cmp_eq_u32 s61, 0
	v_add_f32_dpp v79, v79, v79 row_ror:2 row_mask:0xf bank_mask:0xf bound_ctrl:1
	v_add_f32_dpp v78, v78, v78 row_ror:1 row_mask:0xf bank_mask:0xf bound_ctrl:1
	v_fma_f32 v78, -v184, v81, v78
	v_add_f32_dpp v79, v79, v79 row_ror:1 row_mask:0xf bank_mask:0xf bound_ctrl:1
	v_fma_f32 v79, -v184, v82, v79
	v_sub_f32_e32 v78, v78, v157
	v_sub_f32_e32 v79, v79, v156
	v_exp_f32_e32 v78, v78
	v_exp_f32_e32 v79, v79
	s_cselect_b32 s1, 2, 1
	v_cvt_f32_ubyte0_e32 v197, s1
	v_cvt_f32_ubyte0_e32 v196, s47
	v_pk_mul_f32 v[78:79], v[78:79], v[196:197]
	v_pk_mul_f32 v[196:197], v[62:63], v[128:129]
	v_mul_f32_e32 v193, v184, v193
	v_add_f32_e32 v80, v196, v197
	v_add_f32_e32 v80, v198, v80
	v_add_f32_e32 v80, v199, v80
	s_cmpk_gt_u32 s0, 0x784
	s_cselect_b64 s[90:91], -1, 0
	v_add_f32_dpp v80, v80, v80 row_ror:8 row_mask:0xf bank_mask:0xf bound_ctrl:1
	s_cmp_lg_u64 s[90:91], 0
	s_addc_u32 s1, s28, 0
	v_add_f32_dpp v80, v80, v80 row_ror:4 row_mask:0xf bank_mask:0xf bound_ctrl:1
	v_pk_fma_f32 v[4:5], v[60:61], v[76:77], v[4:5] op_sel_hi:[1,0,1]
	v_pk_fma_f32 v[2:3], v[58:59], v[76:77], v[2:3] op_sel_hi:[1,0,1]
	v_add_f32_dpp v80, v80, v80 row_ror:2 row_mask:0xf bank_mask:0xf bound_ctrl:1
	v_pk_fma_f32 v[8:9], v[60:61], v[76:77], v[8:9] op_sel:[0,1,0]
	v_pk_fma_f32 v[6:7], v[58:59], v[76:77], v[6:7] op_sel:[0,1,0]
	v_add_f32_dpp v80, v80, v80 row_ror:1 row_mask:0xf bank_mask:0xf bound_ctrl:1
	v_sub_f32_e32 v80, v80, v193
	v_sub_f32_e32 v80, v80, v187
	v_exp_f32_e32 v80, v80
	v_pk_fma_f32 v[12:13], v[60:61], v[78:79], v[12:13] op_sel_hi:[1,0,1]
	v_pk_fma_f32 v[10:11], v[58:59], v[78:79], v[10:11] op_sel_hi:[1,0,1]
	v_pk_fma_f32 v[16:17], v[60:61], v[78:79], v[16:17] op_sel:[0,1,0]
	v_mul_f32_e32 v80, v80, v174
	v_pk_fma_f32 v[14:15], v[58:59], v[78:79], v[14:15] op_sel:[0,1,0]
	v_pk_fma_f32 v[20:21], v[60:61], v[80:81], v[20:21] op_sel_hi:[1,0,1]
	s_cmp_eq_u32 s1, 0
	v_pk_fma_f32 v[18:19], v[58:59], v[80:81], v[18:19] op_sel_hi:[1,0,1]
	s_cbranch_scc1 .LBB0_1180
	v_pk_mul_f32 v[196:197], v[62:63], v[126:127]
	v_pk_mul_f32 v[198:199], v[64:65], v[124:125]
	v_add_f32_e32 v83, v196, v197
	v_add_f32_e32 v83, v198, v83
	v_add_f32_e32 v83, v199, v83
	v_cvt_f32_ubyte0_e32 v193, s1
	s_nop 0
	v_add_f32_dpp v83, v83, v83 row_ror:8 row_mask:0xf bank_mask:0xf bound_ctrl:1
	s_nop 1
	v_add_f32_dpp v83, v83, v83 row_ror:4 row_mask:0xf bank_mask:0xf bound_ctrl:1
	s_nop 1
	v_add_f32_dpp v83, v83, v83 row_ror:2 row_mask:0xf bank_mask:0xf bound_ctrl:1
	s_nop 1
	v_add_f32_dpp v83, v83, v83 row_ror:1 row_mask:0xf bank_mask:0xf bound_ctrl:1
	v_fma_f32 v83, -v184, v114, v83
	v_sub_f32_e32 v83, v83, v186
	v_exp_f32_e32 v83, v83
	s_nop 0
	v_mul_f32_e32 v114, v83, v193
	v_fmac_f32_e32 v151, v83, v193
	v_pk_fma_f32 v[24:25], v[60:61], v[114:115], v[24:25] op_sel_hi:[1,0,1]
	v_pk_fma_f32 v[22:23], v[58:59], v[114:115], v[22:23] op_sel_hi:[1,0,1]

; __device__ __forceinline__ float row_sum_f(float v) { v += dpp_f<0x128>(v); v += dpp_f<0x124>(v); v += dpp_f<0x122>(v); v += dpp_f<0x121>(v); return v; }
; __device__ __forceinline__ void stream_task(const Args& a, const int task, const int wave, const float kbA, LAS unsigned* rb, unsigned& ep) {
;     ...
; #pragma unroll
;                 for (int u = 0; u < 4; ++u) {
;                     const int r = wave + 4 * (n0 + u);
;                     { const size_t wo = (size_t)(r - DS) * 512; __builtin_nontemporal_store(k4[u], (f32x4*)(ko + wo)); __builtin_nontemporal_store(v4[u], (f32x4*)(vo + wo)); }
; #pragma unroll
;                     for (int i = 0; i < 8; ++i) {
;                         const int dist = LA + i - r;
;                         const int mult = (dist <= 128 ? 1 : 0) + ((dist & 3) == 0 ? 1 : 0) + ((dist & 15) == 0 ? 1 : 0);
;                         if (mult) {
;                             const float dot = row_sum_f(q[i][0] * k4[u][0] + q[i][1] * k4[u][1] + q[i][2] * k4[u][2] + q[i][3] * k4[u][3]);
;                             const float pp = __builtin_amdgcn_exp2f(dot - slope2 * (float)dist - M[i]) * (float)mult;
;                             l[i] += pp; O[i] = O[i] + v4[u] * pp;
;                         }
.LBB0_1184:
	v_add_co_u32_e32 v60, vcc, 0x6840000, v154
	v_pk_mul_f32 v[62:63], v[56:57], v[40:41]
	v_addc_co_u32_e32 v61, vcc, 0, v155, vcc
	global_store_dwordx4 v[60:61], v[54:57], off nt
	v_add_co_u32_e32 v60, vcc, 0x26840000, v154
	s_sub_i32 s90, 0x7f8, s20
	s_nop 0
	v_addc_co_u32_e32 v61, vcc, 0, v155, vcc
	global_store_dwordx4 v[60:61], v[46:49], off nt
	v_pk_mul_f32 v[60:61], v[54:55], v[38:39]
	v_add_f32_e32 v86, v86, v66
	v_add_f32_e32 v60, v60, v61
	v_add_f32_e32 v60, v62, v60
	v_add_f32_e32 v60, v63, v60
	v_cvt_f32_i32_e32 v61, s90
	v_pk_add_f32 v[64:65], v[86:87], v[76:77]
	v_add_f32_dpp v60, v60, v60 row_ror:8 row_mask:0xf bank_mask:0xf bound_ctrl:1
	v_pk_mul_f32 v[62:63], v[56:57], v[36:37]
	s_sub_i32 s91, 0x7f9, s20
	v_add_f32_dpp v60, v60, v60 row_ror:4 row_mask:0xf bank_mask:0xf bound_ctrl:1
	s_sub_i32 s0, 0x7fa, s20
	v_pk_add_f32 v[58:59], v[148:149], v[78:79]
	v_add_f32_dpp v60, v60, v60 row_ror:2 row_mask:0xf bank_mask:0xf bound_ctrl:1
	s_sub_i32 s1, 0x7fb, s20
	s_add_i32 s47, s55, -11
	v_add_f32_dpp v60, v60, v60 row_ror:1 row_mask:0xf bank_mask:0xf bound_ctrl:1
	v_fma_f32 v60, -v184, v61, v60
	v_sub_f32_e32 v60, v60, v191
	v_exp_f32_e32 v76, v60
	v_pk_mul_f32 v[60:61], v[54:55], v[34:35]
	v_mul_f32_e32 v83, v184, v81
	v_add_f32_e32 v60, v60, v61
	v_add_f32_e32 v60, v62, v60
	v_add_f32_e32 v60, v63, v60
	v_cvt_f32_i32_e32 v61, s91
	v_pk_mul_f32 v[62:63], v[56:57], v[140:141]
	v_add_f32_dpp v60, v60, v60 row_ror:8 row_mask:0xf bank_mask:0xf bound_ctrl:1
	v_add_f32_e32 v150, v150, v80
	v_pk_mul_f32 v[80:81], v[56:57], v[124:125]
	v_add_f32_dpp v60, v60, v60 row_ror:4 row_mask:0xf bank_mask:0xf bound_ctrl:1
	v_mul_f32_e32 v82, v184, v82
	s_mov_b32 s61, s60
	v_add_f32_dpp v60, v60, v60 row_ror:2 row_mask:0xf bank_mask:0xf bound_ctrl:1
	s_and_b64 s[90:91], s[90:91], s[60:61]
	s_nop 0
	v_add_f32_dpp v60, v60, v60 row_ror:1 row_mask:0xf bank_mask:0xf bound_ctrl:1
	v_fma_f32 v60, -v184, v61, v60
	v_sub_f32_e32 v60, v60, v190
	v_exp_f32_e32 v77, v60
	v_pk_mul_f32 v[60:61], v[54:55], v[142:143]
	s_nop 0
	v_add_f32_e32 v60, v60, v61
	v_add_f32_e32 v60, v62, v60
	v_add_f32_e32 v60, v63, v60
	v_cvt_f32_i32_e32 v61, s0
	v_pk_mul_f32 v[62:63], v[56:57], v[138:139]
	v_add_f32_dpp v60, v60, v60 row_ror:8 row_mask:0xf bank_mask:0xf bound_ctrl:1
	s_nop 1
	v_add_f32_dpp v60, v60, v60 row_ror:4 row_mask:0xf bank_mask:0xf bound_ctrl:1
	s_nop 1
	v_add_f32_dpp v60, v60, v60 row_ror:2 row_mask:0xf bank_mask:0xf bound_ctrl:1
	s_nop 1
	v_add_f32_dpp v60, v60, v60 row_ror:1 row_mask:0xf bank_mask:0xf bound_ctrl:1
	v_fma_f32 v60, -v184, v61, v60
	v_sub_f32_e32 v60, v60, v157
	v_exp_f32_e32 v78, v60
	v_pk_mul_f32 v[60:61], v[54:55], v[136:137]
	s_nop 0
	v_add_f32_e32 v60, v60, v61
	v_add_f32_e32 v60, v62, v60
	v_add_f32_e32 v60, v63, v60
	v_cvt_f32_i32_e32 v61, s1
	v_pk_mul_f32 v[62:63], v[56:57], v[130:131]
	v_add_f32_dpp v60, v60, v60 row_ror:8 row_mask:0xf bank_mask:0xf bound_ctrl:1
	s_nop 1
	v_add_f32_dpp v60, v60, v60 row_ror:4 row_mask:0xf bank_mask:0xf bound_ctrl:1
	s_nop 1
	v_add_f32_dpp v60, v60, v60 row_ror:2 row_mask:0xf bank_mask:0xf bound_ctrl:1
	s_nop 1
	v_add_f32_dpp v60, v60, v60 row_ror:1 row_mask:0xf bank_mask:0xf bound_ctrl:1
	v_fma_f32 v60, -v184, v61, v60
	v_sub_f32_e32 v60, v60, v156
	v_exp_f32_e32 v79, v60
	v_pk_mul_f32 v[60:61], v[54:55], v[128:129]
	s_nop 0
	v_add_f32_e32 v60, v60, v61
	v_add_f32_e32 v60, v62, v60
	v_add_f32_e32 v60, v63, v60
	v_cvt_f32_i32_e32 v61, s47
	s_add_i32 s47, s55, -10
	v_add_f32_dpp v60, v60, v60 row_ror:8 row_mask:0xf bank_mask:0xf bound_ctrl:1
	s_nop 1
	v_add_f32_dpp v60, v60, v60 row_ror:4 row_mask:0xf bank_mask:0xf bound_ctrl:1
	s_nop 1
	v_add_f32_dpp v60, v60, v60 row_ror:2 row_mask:0xf bank_mask:0xf bound_ctrl:1
	s_nop 1
	v_add_f32_dpp v60, v60, v60 row_ror:1 row_mask:0xf bank_mask:0xf bound_ctrl:1
	v_fma_f32 v60, -v184, v61, v60
	v_sub_f32_e32 v60, v60, v187
	v_exp_f32_e32 v62, v60
	v_pk_mul_f32 v[60:61], v[54:55], v[126:127]
	s_nop 0
	v_add_f32_e32 v60, v60, v61
	v_add_f32_e32 v60, v80, v60
	v_add_f32_e32 v60, v81, v60
	v_cvt_f32_i32_e32 v61, s47
	v_pk_mul_f32 v[80:81], v[56:57], v[120:121]
	v_add_f32_dpp v60, v60, v60 row_ror:8 row_mask:0xf bank_mask:0xf bound_ctrl:1
	v_pk_mul_f32 v[56:57], v[56:57], v[134:135]
	s_mov_b32 s47, 0x6842000
	v_add_f32_dpp v60, v60, v60 row_ror:4 row_mask:0xf bank_mask:0xf bound_ctrl:1
	s_nop 1
	v_add_f32_dpp v60, v60, v60 row_ror:2 row_mask:0xf bank_mask:0xf bound_ctrl:1
	s_nop 1
	v_add_f32_dpp v60, v60, v60 row_ror:1 row_mask:0xf bank_mask:0xf bound_ctrl:1
	v_fma_f32 v60, -v184, v61, v60
	v_sub_f32_e32 v60, v60, v186
	v_exp_f32_e32 v63, v60
	v_pk_mul_f32 v[60:61], v[54:55], v[122:123]
	v_pk_mul_f32 v[54:55], v[54:55], v[132:133]
	v_add_f32_e32 v60, v60, v61
	v_add_f32_e32 v54, v54, v55
	v_add_f32_e32 v54, v56, v54
	v_add_f32_e32 v54, v57, v54
	v_pk_mul_f32 v[56:57], v[52:53], v[40:41]
	v_add_f32_e32 v60, v80, v60
	v_add_f32_dpp v54, v54, v54 row_ror:8 row_mask:0xf bank_mask:0xf bound_ctrl:1
	v_add_f32_e32 v60, v81, v60
	v_pk_mul_f32 v[80:81], v[52:53], v[36:37]
	v_add_f32_dpp v54, v54, v54 row_ror:4 row_mask:0xf bank_mask:0xf bound_ctrl:1
	v_add_f32_dpp v60, v60, v60 row_ror:8 row_mask:0xf bank_mask:0xf bound_ctrl:1
	s_nop 0
	v_add_f32_dpp v54, v54, v54 row_ror:2 row_mask:0xf bank_mask:0xf bound_ctrl:1
	v_add_f32_dpp v60, v60, v60 row_ror:4 row_mask:0xf bank_mask:0xf bound_ctrl:1
	s_nop 0
	v_add_f32_dpp v54, v54, v54 row_ror:1 row_mask:0xf bank_mask:0xf bound_ctrl:1
	v_sub_f32_e32 v54, v54, v82
	v_sub_f32_e32 v54, v54, v91
	v_exp_f32_e32 v61, v54
	v_add_co_u32_e32 v54, vcc, s47, v154
	s_mov_b32 s47, 0x26842000
	s_nop 0
	v_addc_co_u32_e32 v55, vcc, 0, v155, vcc
; __device__ __forceinline__ float row_sum_f(float v) { v += dpp_f<0x128>(v); v += dpp_f<0x124>(v); v += dpp_f<0x122>(v); v += dpp_f<0x121>(v); return v; }
; __device__ __forceinline__ void stream_task(const Args& a, const int task, const int wave, const float kbA, LAS unsigned* rb, unsigned& ep) {
;     ...
; #pragma unroll
;                 for (int u = 0; u < 4; ++u) {
;                     const int r = wave + 4 * (n0 + u);
;                     { const size_t wo = (size_t)(r - DS) * 512; __builtin_nontemporal_store(k4[u], (f32x4*)(ko + wo)); __builtin_nontemporal_store(v4[u], (f32x4*)(vo + wo)); }
; #pragma unroll
;                     for (int i = 0; i < 8; ++i) {
;                         const int dist = LA + i - r;
;                         const int mult = (dist <= 128 ? 1 : 0) + ((dist & 3) == 0 ? 1 : 0) + ((dist & 15) == 0 ? 1 : 0);
;                         if (mult) {
;                             const float dot = row_sum_f(q[i][0] * k4[u][0] + q[i][1] * k4[u][1] + q[i][2] * k4[u][2] + q[i][3] * k4[u][3]);
;                             const float pp = __builtin_amdgcn_exp2f(dot - slope2 * (float)dist - M[i]) * (float)mult;
;                             l[i] += pp; O[i] = O[i] + v4[u] * pp;
;                         }
	global_store_dwordx4 v[54:55], v[50:53], off nt
	v_add_co_u32_e32 v54, vcc, s47, v154
	v_add_f32_dpp v60, v60, v60 row_ror:2 row_mask:0xf bank_mask:0xf bound_ctrl:1
	s_nop 0
	v_addc_co_u32_e32 v55, vcc, 0, v155, vcc
	global_store_dwordx4 v[54:55], v[42:45], off nt
	v_pk_mul_f32 v[54:55], v[50:51], v[38:39]
	s_sub_i32 vcc_lo, 0x7f4, s20
	v_add_f32_e32 v54, v54, v55
	v_add_f32_e32 v54, v56, v54
	v_add_f32_e32 v54, v57, v54
	v_cvt_f32_i32_e32 v55, vcc_lo
	v_pk_mul_f32 v[56:57], v[50:51], v[34:35]
	v_add_f32_dpp v54, v54, v54 row_ror:8 row_mask:0xf bank_mask:0xf bound_ctrl:1
	s_sub_i32 vcc_hi, 0x7f5, s20
	s_cmp_eq_u32 s91, 0
	v_add_f32_dpp v54, v54, v54 row_ror:4 row_mask:0xf bank_mask:0xf bound_ctrl:1
	s_cselect_b64 s[62:63], -1, 0
	s_cmp_eq_u32 s90, 0
	v_add_f32_dpp v54, v54, v54 row_ror:2 row_mask:0xf bank_mask:0xf bound_ctrl:1
	s_cselect_b64 s[90:91], -1, 0
	s_cmp_lg_u64 s[90:91], 0
	v_add_f32_dpp v54, v54, v54 row_ror:1 row_mask:0xf bank_mask:0xf bound_ctrl:1
	v_fma_f32 v54, -v184, v55, v54
	v_add_f32_e32 v55, v56, v57
	v_add_f32_e32 v55, v80, v55
	v_add_f32_e32 v55, v81, v55
	v_cvt_f32_i32_e32 v56, vcc_hi
	s_addc_u32 s47, s97, 0
	v_add_f32_dpp v55, v55, v55 row_ror:8 row_mask:0xf bank_mask:0xf bound_ctrl:1
	s_cmp_lg_u64 s[62:63], 0
	v_sub_f32_e32 v54, v54, v191
	v_add_f32_dpp v55, v55, v55 row_ror:4 row_mask:0xf bank_mask:0xf bound_ctrl:1
	s_addc_u32 s61, s96, 0
	v_exp_f32_e32 v54, v54
	v_add_f32_dpp v55, v55, v55 row_ror:2 row_mask:0xf bank_mask:0xf bound_ctrl:1
	v_cvt_f32_ubyte0_e32 v57, s61
	v_add_f32_dpp v60, v60, v60 row_ror:1 row_mask:0xf bank_mask:0xf bound_ctrl:1
	v_add_f32_dpp v55, v55, v55 row_ror:1 row_mask:0xf bank_mask:0xf bound_ctrl:1
	v_fma_f32 v55, -v184, v56, v55
	v_cvt_f32_ubyte0_e32 v56, s47
	s_mov_b32 s47, s46
	v_sub_f32_e32 v55, v55, v190
	s_and_b64 s[62:63], vcc, s[46:47]
	v_exp_f32_e32 v55, v55
	s_cmp_eq_u32 s62, 0
	s_cselect_b32 s47, 2, 1
	s_cmp_eq_u32 s63, 0
	s_cselect_b32 s61, 2, 1
	v_pk_mul_f32 v[80:81], v[76:77], v[56:57]
	v_pk_fma_f32 v[56:57], v[76:77], v[56:57], v[64:65]
	v_cvt_f32_ubyte0_e32 v65, s61
	v_cvt_f32_ubyte0_e32 v64, s47
	v_pk_mul_f32 v[76:77], v[54:55], v[64:65]
	v_pk_fma_f32 v[86:87], v[54:55], v[64:65], v[56:57]
	v_pk_mul_f32 v[54:55], v[50:51], v[142:143]
	v_pk_mul_f32 v[56:57], v[52:53], v[140:141]
	v_add_f32_e32 v54, v54, v55
	v_add_f32_e32 v54, v56, v54
	s_sub_i32 s47, s55, 17
	v_add_f32_e32 v54, v57, v54
	v_cvt_f32_i32_e32 v55, s47
	s_and_b32 s61, s47, 3
	v_add_f32_dpp v54, v54, v54 row_ror:8 row_mask:0xf bank_mask:0xf bound_ctrl:1
	v_pk_mul_f32 v[56:57], v[50:51], v[136:137]
	s_cmp_eq_u32 s61, 0
	v_add_f32_dpp v54, v54, v54 row_ror:4 row_mask:0xf bank_mask:0xf bound_ctrl:1
	v_pk_mul_f32 v[64:65], v[52:53], v[138:139]
	s_cselect_b32 s61, 2, 1
	v_add_f32_dpp v54, v54, v54 row_ror:2 row_mask:0xf bank_mask:0xf bound_ctrl:1
	v_cvt_f32_ubyte0_e32 v114, s61
	s_add_i32 s47, s55, -16
	v_add_f32_dpp v54, v54, v54 row_ror:1 row_mask:0xf bank_mask:0xf bound_ctrl:1
	v_fma_f32 v54, -v184, v55, v54
	v_add_f32_e32 v55, v56, v57
	v_add_f32_e32 v55, v64, v55
	v_add_f32_e32 v55, v65, v55
	s_mov_b32 s61, 11
	v_cvt_f32_i32_e32 v56, s47
	v_add_f32_dpp v55, v55, v55 row_ror:8 row_mask:0xf bank_mask:0xf bound_ctrl:1
	s_and_b64 s[0:1], s[0:1], s[60:61]
	s_cmp_eq_u32 s1, 0
	v_add_f32_dpp v55, v55, v55 row_ror:4 row_mask:0xf bank_mask:0xf bound_ctrl:1
	s_cselect_b64 s[62:63], -1, 0
	s_cmp_eq_u32 s0, 0
	v_add_f32_dpp v55, v55, v55 row_ror:2 row_mask:0xf bank_mask:0xf bound_ctrl:1
	s_cselect_b64 s[0:1], -1, 0
	s_cmp_lg_u64 s[0:1], 0
	v_add_f32_dpp v55, v55, v55 row_ror:1 row_mask:0xf bank_mask:0xf bound_ctrl:1
	v_fma_f32 v55, -v184, v56, v55
	v_sub_f32_e32 v54, v54, v157
	v_sub_f32_e32 v55, v55, v156
	s_addc_u32 s0, s29, 0
	v_exp_f32_e32 v54, v54
	v_exp_f32_e32 v55, v55
	s_cmp_lg_u64 s[62:63], 0
	s_addc_u32 s1, s45, 0
	v_cvt_f32_ubyte0_e32 v57, s1
	v_cvt_f32_ubyte0_e32 v56, s0
	v_pk_mul_f32 v[64:65], v[78:79], v[56:57]
	v_pk_fma_f32 v[56:57], v[78:79], v[56:57], v[58:59]
	v_pk_mul_f32 v[58:59], v[54:55], v[114:115]
	v_pk_fma_f32 v[148:149], v[54:55], v[114:115], v[56:57]
	v_pk_mul_f32 v[54:55], v[50:51], v[128:129]
	v_pk_mul_f32 v[56:57], v[52:53], v[130:131]
	v_add_f32_e32 v54, v54, v55
	v_add_f32_e32 v54, v56, v54
	s_add_i32 s0, s55, -15
	v_add_f32_e32 v54, v57, v54
	v_cvt_f32_i32_e32 v55, s0
	v_pk_mul_f32 v[56:57], v[50:51], v[126:127]
	v_add_f32_dpp v54, v54, v54 row_ror:8 row_mask:0xf bank_mask:0xf bound_ctrl:1
	v_pk_fma_f32 v[10:11], v[46:47], v[64:65], v[10:11] op_sel_hi:[1,0,1]
	v_pk_fma_f32 v[12:13], v[48:49], v[64:65], v[12:13] op_sel_hi:[1,0,1]
	v_add_f32_dpp v54, v54, v54 row_ror:4 row_mask:0xf bank_mask:0xf bound_ctrl:1
	v_pk_fma_f32 v[14:15], v[46:47], v[64:65], v[14:15] op_sel:[0,1,0]
	v_pk_fma_f32 v[16:17], v[48:49], v[64:65], v[16:17] op_sel:[0,1,0]
; __device__ __forceinline__ float row_sum_f(float v) { v += dpp_f<0x128>(v); v += dpp_f<0x124>(v); v += dpp_f<0x122>(v); v += dpp_f<0x121>(v); return v; }
; __device__ __forceinline__ void stream_task(const Args& a, const int task, const int wave, const float kbA, LAS unsigned* rb, unsigned& ep) {
;     ...
; #pragma unroll
;                 for (int u = 0; u < 4; ++u) {
;                     const int r = wave + 4 * (n0 + u);
;                     { const size_t wo = (size_t)(r - DS) * 512; __builtin_nontemporal_store(k4[u], (f32x4*)(ko + wo)); __builtin_nontemporal_store(v4[u], (f32x4*)(vo + wo)); }
; #pragma unroll
;                     for (int i = 0; i < 8; ++i) {
;                         const int dist = LA + i - r;
;                         const int mult = (dist <= 128 ? 1 : 0) + ((dist & 3) == 0 ? 1 : 0) + ((dist & 15) == 0 ? 1 : 0);
;                         if (mult) {
;                             const float dot = row_sum_f(q[i][0] * k4[u][0] + q[i][1] * k4[u][1] + q[i][2] * k4[u][2] + q[i][3] * k4[u][3]);
;                             const float pp = __builtin_amdgcn_exp2f(dot - slope2 * (float)dist - M[i]) * (float)mult;
;                             l[i] += pp; O[i] = O[i] + v4[u] * pp;
;                         }
;                     }
;                 }
;             }
	v_add_f32_dpp v54, v54, v54 row_ror:2 row_mask:0xf bank_mask:0xf bound_ctrl:1
	v_pk_mul_f32 v[64:65], v[52:53], v[124:125]
	s_add_i32 s0, s55, -14
	v_add_f32_dpp v54, v54, v54 row_ror:1 row_mask:0xf bank_mask:0xf bound_ctrl:1
	v_fma_f32 v54, -v184, v55, v54
	v_add_f32_e32 v55, v56, v57
	v_add_f32_e32 v55, v64, v55
	v_add_f32_e32 v55, v65, v55
	v_cvt_f32_i32_e32 v56, s0
	v_sub_f32_e32 v54, v54, v187
	v_add_f32_dpp v55, v55, v55 row_ror:8 row_mask:0xf bank_mask:0xf bound_ctrl:1
	v_exp_f32_e32 v54, v54
	s_add_i32 s0, s55, -13
	v_add_f32_dpp v55, v55, v55 row_ror:4 row_mask:0xf bank_mask:0xf bound_ctrl:1
	v_sub_f32_e32 v60, v60, v83
	v_sub_f32_e32 v60, v60, v185
	v_add_f32_dpp v55, v55, v55 row_ror:2 row_mask:0xf bank_mask:0xf bound_ctrl:1
	s_add_i32 s2, s2, 4
	v_exp_f32_e32 v60, v60
	v_add_f32_dpp v55, v55, v55 row_ror:1 row_mask:0xf bank_mask:0xf bound_ctrl:1
	v_fma_f32 v55, -v184, v56, v55
	v_sub_f32_e32 v55, v55, v186
	v_exp_f32_e32 v55, v55
	v_pk_mul_f32 v[56:57], v[62:63], v[110:111]
	v_pk_fma_f32 v[62:63], v[62:63], v[110:111], v[150:151]
	v_pk_fma_f32 v[18:19], v[46:47], v[56:57], v[18:19] op_sel_hi:[1,0,1]
	v_pk_fma_f32 v[20:21], v[48:49], v[56:57], v[20:21] op_sel_hi:[1,0,1]
	v_pk_fma_f32 v[22:23], v[46:47], v[56:57], v[22:23] op_sel:[0,1,0]
	v_pk_fma_f32 v[24:25], v[48:49], v[56:57], v[24:25] op_sel:[0,1,0]
	v_pk_mul_f32 v[56:57], v[54:55], v[110:111]
	v_pk_fma_f32 v[150:151], v[54:55], v[110:111], v[62:63]
	v_pk_mul_f32 v[54:55], v[50:51], v[122:123]
	v_pk_mul_f32 v[50:51], v[50:51], v[132:133]
	v_pk_mul_f32 v[62:63], v[52:53], v[120:121]
	v_add_f32_e32 v54, v54, v55
	v_pk_mul_f32 v[52:53], v[52:53], v[134:135]
	v_add_f32_e32 v50, v50, v51
	v_add_f32_e32 v54, v62, v54
	v_add_f32_e32 v50, v52, v50
	v_add_f32_e32 v54, v63, v54
	v_cvt_f32_i32_e32 v55, s0
	s_add_i32 s0, s55, -12
	v_add_f32_e32 v50, v53, v50
	v_add_f32_dpp v54, v54, v54 row_ror:8 row_mask:0xf bank_mask:0xf bound_ctrl:1
	v_cvt_f32_i32_e32 v51, s0
	v_add_f32_dpp v50, v50, v50 row_ror:8 row_mask:0xf bank_mask:0xf bound_ctrl:1
	v_add_f32_dpp v54, v54, v54 row_ror:4 row_mask:0xf bank_mask:0xf bound_ctrl:1
	s_add_u32 s88, s88, 0x8000
	v_add_f32_dpp v50, v50, v50 row_ror:4 row_mask:0xf bank_mask:0xf bound_ctrl:1
	v_add_f32_dpp v54, v54, v54 row_ror:2 row_mask:0xf bank_mask:0xf bound_ctrl:1
	s_addc_u32 s89, s89, 0
	v_add_f32_dpp v50, v50, v50 row_ror:2 row_mask:0xf bank_mask:0xf bound_ctrl:1
	v_add_f32_dpp v54, v54, v54 row_ror:1 row_mask:0xf bank_mask:0xf bound_ctrl:1
	v_fma_f32 v54, -v184, v55, v54
	v_add_f32_dpp v50, v50, v50 row_ror:1 row_mask:0xf bank_mask:0xf bound_ctrl:1
	v_fma_f32 v50, -v184, v51, v50
	v_sub_f32_e32 v54, v54, v185
	v_sub_f32_e32 v50, v50, v91
	v_exp_f32_e32 v54, v54
	v_exp_f32_e32 v55, v50
	s_add_i32 s20, s20, 16
	s_add_u32 s18, s18, 0x8000
	s_addc_u32 s19, s19, 0
	v_pk_mul_f32 v[50:51], v[60:61], v[112:113]
	s_add_u32 s16, s16, 0x8000
	v_pk_fma_f32 v[2:3], v[46:47], v[80:81], v[2:3] op_sel_hi:[1,0,1]
	v_pk_fma_f32 v[4:5], v[48:49], v[80:81], v[4:5] op_sel_hi:[1,0,1]
	v_pk_fma_f32 v[6:7], v[46:47], v[80:81], v[6:7] op_sel:[0,1,0]
	v_pk_fma_f32 v[8:9], v[48:49], v[80:81], v[8:9] op_sel:[0,1,0]
	v_pk_fma_f32 v[52:53], v[60:61], v[112:113], v[84:85]
	v_pk_fma_f32 v[26:27], v[46:47], v[50:51], v[26:27] op_sel_hi:[1,0,1]
	v_pk_fma_f32 v[28:29], v[48:49], v[50:51], v[28:29] op_sel_hi:[1,0,1]
	v_pk_fma_f32 v[30:31], v[46:47], v[50:51], v[30:31] op_sel:[0,1,0]
	v_pk_fma_f32 v[32:33], v[48:49], v[50:51], v[32:33] op_sel:[0,1,0]
	v_pk_mul_f32 v[46:47], v[54:55], v[112:113]
	s_addc_u32 s17, s17, 0
	v_pk_fma_f32 v[4:5], v[44:45], v[76:77], v[4:5] op_sel_hi:[1,0,1]
	v_pk_fma_f32 v[2:3], v[42:43], v[76:77], v[2:3] op_sel_hi:[1,0,1]
	v_pk_fma_f32 v[8:9], v[44:45], v[76:77], v[8:9] op_sel:[0,1,0]
	v_pk_fma_f32 v[6:7], v[42:43], v[76:77], v[6:7] op_sel:[0,1,0]
	v_pk_fma_f32 v[12:13], v[44:45], v[58:59], v[12:13] op_sel_hi:[1,0,1]
	v_pk_fma_f32 v[10:11], v[42:43], v[58:59], v[10:11] op_sel_hi:[1,0,1]
	v_pk_fma_f32 v[16:17], v[44:45], v[58:59], v[16:17] op_sel:[0,1,0]
	v_pk_fma_f32 v[14:15], v[42:43], v[58:59], v[14:15] op_sel:[0,1,0]
	v_pk_fma_f32 v[20:21], v[44:45], v[56:57], v[20:21] op_sel_hi:[1,0,1]
	v_pk_fma_f32 v[18:19], v[42:43], v[56:57], v[18:19] op_sel_hi:[1,0,1]
	v_pk_fma_f32 v[24:25], v[44:45], v[56:57], v[24:25] op_sel:[0,1,0]
	v_pk_fma_f32 v[22:23], v[42:43], v[56:57], v[22:23] op_sel:[0,1,0]
	v_pk_fma_f32 v[28:29], v[44:45], v[46:47], v[28:29] op_sel_hi:[1,0,1]
	v_pk_fma_f32 v[26:27], v[42:43], v[46:47], v[26:27] op_sel_hi:[1,0,1]
	v_pk_fma_f32 v[84:85], v[54:55], v[112:113], v[52:53]
	v_pk_fma_f32 v[32:33], v[44:45], v[46:47], v[32:33] op_sel:[0,1,0]
	s_cmpk_gt_u32 s2, 0x1fb
	v_pk_fma_f32 v[30:31], v[42:43], v[46:47], v[30:31] op_sel:[0,1,0]
	s_cbranch_scc1 .LBB0_1186
	s_mov_b32 s55, s47
	s_branch .LBB0_1164
